# adds: P2 conv-weight staging loads issued together (was a serialized load-wait-ds_write loop)
# speedup vs baseline: 1.4763x; 1.0087x over previous
.LBB0_743:
	v_mov_b32_e32 v6, v0
	s_movk_i32 s0, 0xd80
	s_nop 0
	v_cmp_gt_i32_e32 vcc, s0, v6
	s_and_saveexec_b64 s[0:1], vcc
	s_cbranch_execz .LBB0_748
	v_readlane_b32 s2, v242, 40
	s_mul_hi_u32 s3, s2, 0xba00
	s_mul_i32 s2, s2, 0xba00
	v_readlane_b32 s4, v243, 54
	s_add_u32 s2, s4, s2
	v_readlane_b32 s4, v243, 55
	s_addc_u32 s3, s4, s3
	v_lshlrev_b32_e32 v54, 4, v6
	s_nop 2
	global_load_dwordx4 v[30:33], v54, s[2:3] offset:-8
	v_add_u32_e32 v55, 0x2000, v54
	global_load_dwordx4 v[34:37], v55, s[2:3] offset:-8
	v_add_u32_e32 v55, 0x4000, v54
	global_load_dwordx4 v[38:41], v55, s[2:3] offset:-8
	v_add_u32_e32 v55, 0x6000, v54
	global_load_dwordx4 v[42:45], v55, s[2:3] offset:-8
	v_add_u32_e32 v55, 0x8000, v54
	global_load_dwordx4 v[46:49], v55, s[2:3] offset:-8
	v_mov_b32_e32 v50, 0
	v_mov_b32_e32 v51, 0
	v_mov_b32_e32 v52, 0
	v_mov_b32_e32 v53, 0
	v_mov_b32_e32 v58, 0
	v_mov_b32_e32 v59, 0
	v_mov_b32_e32 v60, 0
	v_mov_b32_e32 v61, 0
	v_cmp_gt_u32_e32 vcc, 0x1a0, v6
	s_and_saveexec_b64 s[4:5], vcc
	s_cbranch_execz .Lstw_k5
	v_add_u32_e32 v55, 0xa000, v54
	global_load_dwordx4 v[50:53], v55, s[2:3] offset:-8
.Lstw_k5:
	s_or_b64 exec, exec, s[4:5]
	s_mov_b32 s6, 0x2aaaaaab
	v_add_u32_e32 v56, 0x0, v6
	v_mul_hi_u32 v57, v56, s6
	v_lshrrev_b32_e32 v57, 4, v57
	v_mul_u32_u24_e32 v62, 0x60, v57
	v_sub_u32_e32 v56, v56, v62
	v_and_b32_e32 v62, 1, v56
	v_lshl_or_b32 v62, v57, 1, v62
	v_lshrrev_b32_e32 v56, 1, v56
	v_mad_u32_u24 v62, v62, 48, v56
	v_lshl_add_u32 v62, v62, 4, 32
	v_add_u32_e32 v56, 0x200, v6
	v_mul_hi_u32 v57, v56, s6
	v_lshrrev_b32_e32 v57, 4, v57
	v_mul_u32_u24_e32 v63, 0x60, v57
	v_sub_u32_e32 v56, v56, v63
	v_and_b32_e32 v63, 1, v56
	v_lshl_or_b32 v63, v57, 1, v63
	v_lshrrev_b32_e32 v56, 1, v56
	v_mad_u32_u24 v63, v63, 48, v56
	v_lshl_add_u32 v63, v63, 4, 32
	v_add_u32_e32 v56, 0x400, v6
	v_mul_hi_u32 v57, v56, s6
	v_lshrrev_b32_e32 v57, 4, v57
	v_mul_u32_u24_e32 v64, 0x60, v57
	v_sub_u32_e32 v56, v56, v64
	v_and_b32_e32 v64, 1, v56
	v_lshl_or_b32 v64, v57, 1, v64
	v_lshrrev_b32_e32 v56, 1, v56
	v_mad_u32_u24 v64, v64, 48, v56
	v_lshl_add_u32 v64, v64, 4, 32
	v_add_u32_e32 v56, 0x600, v6
	v_mul_hi_u32 v57, v56, s6
	v_lshrrev_b32_e32 v57, 4, v57
	v_mul_u32_u24_e32 v65, 0x60, v57
	v_sub_u32_e32 v56, v56, v65
	v_and_b32_e32 v65, 1, v56
	v_lshl_or_b32 v65, v57, 1, v65
	v_lshrrev_b32_e32 v56, 1, v56
	v_mad_u32_u24 v65, v65, 48, v56
	v_lshl_add_u32 v65, v65, 4, 32
	v_add_u32_e32 v56, 0x800, v6
	v_mul_hi_u32 v57, v56, s6
	v_lshrrev_b32_e32 v57, 4, v57
	v_mul_u32_u24_e32 v94, 0x60, v57
	v_sub_u32_e32 v56, v56, v94
	v_and_b32_e32 v94, 1, v56
	v_lshl_or_b32 v94, v57, 1, v94
	v_lshrrev_b32_e32 v56, 1, v56
	v_mad_u32_u24 v94, v94, 48, v56
	v_lshl_add_u32 v94, v94, 4, 32
	v_add_u32_e32 v56, 0xa00, v6
	v_mul_hi_u32 v57, v56, s6
	v_lshrrev_b32_e32 v57, 4, v57
	v_mul_u32_u24_e32 v95, 0x60, v57
	v_sub_u32_e32 v56, v56, v95
	v_and_b32_e32 v95, 1, v56
	v_lshl_or_b32 v95, v57, 1, v95
	v_lshrrev_b32_e32 v56, 1, v56
	v_mad_u32_u24 v95, v95, 48, v56
	v_lshl_add_u32 v95, v95, 4, 32
	v_add_u32_e32 v56, 0xc00, v6
	v_mul_hi_u32 v57, v56, s6
	v_lshrrev_b32_e32 v57, 4, v57
	v_mul_u32_u24_e32 v96, 0x60, v57
	v_sub_u32_e32 v56, v56, v96
	v_and_b32_e32 v96, 1, v56
	v_lshl_or_b32 v96, v57, 1, v96
	v_lshrrev_b32_e32 v56, 1, v56
	v_mad_u32_u24 v96, v96, 48, v56
	v_lshl_add_u32 v96, v96, 4, 32
	s_waitcnt vmcnt(0)
	ds_write_b128 v62, v[30:33]
	ds_write_b128 v63, v[34:37]
	ds_write_b128 v64, v[38:41]
	ds_write_b128 v65, v[42:45]
	ds_write_b128 v94, v[46:49]
	ds_write_b128 v95, v[50:53]
	v_cmp_gt_u32_e32 vcc, 0x180, v6
	s_and_saveexec_b64 s[4:5], vcc
	ds_write_b128 v96, v[58:61]
	s_or_b64 exec, exec, s[4:5]
